# v44 + PV first LDS reads hoisted above softmax exp in all 4 attention loops
# speedup vs baseline: 1.0052x; 1.0041x over previous
; __device__ __forceinline__ unsigned cvt_pk_bf16(float lo, float hi) { unsigned r; asm volatile("v_cvt_pk_bf16_f32 %0, %1, %2" : "=v"(r) : "v"(lo), "v"(hi)); return r; }
; #define LAS __attribute__((address_space(3)))
; template <bool MLA, bool grpB>
; __device__ __forceinline__ void attn_unit_g(LAS unsigned char* lds, const AttnPtrs& P, int b, int h, int qblk) {
;     ...
;         float ps = 0.f;
; #pragma unroll
;         for (int blk = 0; blk < 2; ++blk)
; #pragma unroll
;             for (int r = 0; r < 16; ++r) { const float pv_ = __builtin_amdgcn_exp2f(sc[blk][r] - mref); sc[blk][r] = pv_; ps += pv_; }
;         lrun += ps;
; #pragma unroll
;         for (int blk = 0; blk < 2; ++blk)
; #pragma unroll
;             for (int ks = 0; ks < 2; ++ks) { u32x4 w;
;                 w.x = pg8::cvt_pk_bf16(sc[blk][8 * ks + 0], sc[blk][8 * ks + 1]); w.y = pg8::cvt_pk_bf16(sc[blk][8 * ks + 2], sc[blk][8 * ks + 3]);
;                 w.z = pg8::cvt_pk_bf16(sc[blk][8 * ks + 4], sc[blk][8 * ks + 5]); w.w = pg8::cvt_pk_bf16(sc[blk][8 * ks + 6], sc[blk][8 * ks + 7]);
;                 pb[blk][ks] = __builtin_bit_cast(bf16x8, w); }
;         __builtin_amdgcn_sched_barrier(0);
;     };
;     auto pv = [&](int voff) {
;         const LAS unsigned char* va = lds + varow + voff;
;         bf16x8 a[PFD];
;         auto ld = [&](int i) -> bf16x8 {
;             const int dvb = i & 3, bk = i >> 2, so = ((4 * (bk >> 1) + 2 * hi + (bk & 1)) ^ vswz) * 16;
;             return *(const LAS bf16x8*)(va + 32 * dvb * VROW + so);
;         };
; #pragma unroll
;         for (int i = 0; i < PFD; ++i) a[i] = ld(i);
; #pragma unroll
;         for (int i = 0; i < 16; ++i) {
;             o[i & 3] = __builtin_amdgcn_mfma_f32_32x32x16_bf16(a[i % PFD], pb[i >> 3][(i >> 2) & 1], o[i & 3], 0, 0, 0);
;             if (i + PFD < 16) a[i % PFD] = ld(i + PFD);
;         }
;         __builtin_amdgcn_sched_group_barrier(0x100, PFD, 0);
; #pragma unroll
;         for (int i = 0; i < 16; ++i) { __builtin_amdgcn_sched_group_barrier(0x008, 1, 0); __builtin_amdgcn_sched_group_barrier(0x100, 1, 0); }
;         __builtin_amdgcn_sched_barrier(0);
.LBB0_1216:
	v_add_u32_e32 v246, s21, v187
	v_add_u32_e32 v247, v246, v188
	ds_read_b128 v[210:213], v247
	ds_read_b128 v[214:217], v247 offset:4096
	ds_read_b128 v[218:221], v247 offset:8192
	ds_read_b128 v[222:225], v247 offset:12288
	v_add_u32_e32 v248, v246, v189
	ds_read_b128 v[226:229], v248
	ds_read_b128 v[236:239], v248 offset:4096
	v_sub_f32_e32 v0, v96, v193
	v_exp_f32_e32 v0, v0
	v_sub_f32_e32 v2, v97, v193
	v_exp_f32_e32 v2, v2
	v_sub_f32_e32 v3, v98, v193
	v_exp_f32_e32 v3, v3
	v_sub_f32_e32 v4, v99, v193
	v_exp_f32_e32 v4, v4
	v_sub_f32_e32 v6, v100, v193
	v_add_f32_e32 v5, 0, v0
	v_exp_f32_e32 v6, v6
	v_sub_f32_e32 v7, v101, v193
	v_add_f32_e32 v5, v2, v5
	v_exp_f32_e32 v7, v7
	v_sub_f32_e32 v8, v102, v193
	v_add_f32_e32 v5, v3, v5
	v_exp_f32_e32 v8, v8
	v_sub_f32_e32 v9, v103, v193
	v_add_f32_e32 v5, v4, v5
	v_exp_f32_e32 v9, v9
	v_sub_f32_e32 v10, v104, v193
	v_add_f32_e32 v5, v6, v5
	v_exp_f32_e32 v10, v10
	v_sub_f32_e32 v11, v105, v193
	v_add_f32_e32 v5, v7, v5
	v_exp_f32_e32 v11, v11
	v_sub_f32_e32 v12, v106, v193
	v_add_f32_e32 v5, v8, v5
	v_exp_f32_e32 v12, v12
	v_sub_f32_e32 v13, v107, v193
	v_add_f32_e32 v5, v9, v5
	v_exp_f32_e32 v13, v13
	v_sub_f32_e32 v14, v108, v193
	v_add_f32_e32 v5, v10, v5
	v_exp_f32_e32 v14, v14
	v_sub_f32_e32 v15, v109, v193
	v_add_f32_e32 v5, v11, v5
	v_exp_f32_e32 v15, v15
	v_sub_f32_e32 v96, v110, v193
	v_add_f32_e32 v5, v12, v5
	v_exp_f32_e32 v96, v96
	v_sub_f32_e32 v97, v111, v193
	v_add_f32_e32 v5, v13, v5
	v_exp_f32_e32 v97, v97
	v_sub_f32_e32 v80, v80, v193
	v_add_f32_e32 v5, v14, v5
	v_exp_f32_e32 v80, v80
	v_sub_f32_e32 v81, v81, v193
	v_add_f32_e32 v5, v15, v5
	v_exp_f32_e32 v81, v81
	v_sub_f32_e32 v82, v82, v193
	v_add_f32_e32 v5, v96, v5
	v_exp_f32_e32 v82, v82
	v_sub_f32_e32 v83, v83, v193
	v_add_f32_e32 v5, v97, v5
	v_exp_f32_e32 v83, v83
	v_sub_f32_e32 v84, v84, v193
	v_add_f32_e32 v5, v80, v5
	v_exp_f32_e32 v84, v84
	v_sub_f32_e32 v85, v85, v193
	v_add_f32_e32 v5, v81, v5
	v_exp_f32_e32 v85, v85
	v_sub_f32_e32 v86, v86, v193
	v_add_f32_e32 v5, v82, v5
	v_exp_f32_e32 v86, v86
	v_sub_f32_e32 v87, v87, v193
	v_add_f32_e32 v5, v83, v5
	v_exp_f32_e32 v87, v87
	v_sub_f32_e32 v88, v88, v193
	v_add_f32_e32 v5, v84, v5
	v_exp_f32_e32 v88, v88
	v_sub_f32_e32 v89, v89, v193
	v_add_f32_e32 v5, v85, v5
	v_exp_f32_e32 v89, v89
	v_sub_f32_e32 v90, v90, v193
	v_add_f32_e32 v5, v86, v5
	v_exp_f32_e32 v90, v90
	v_sub_f32_e32 v91, v91, v193
	v_add_f32_e32 v5, v87, v5
	v_exp_f32_e32 v91, v91
	v_sub_f32_e32 v92, v92, v193
	v_add_f32_e32 v5, v88, v5
	v_exp_f32_e32 v92, v92
	v_sub_f32_e32 v93, v93, v193
	v_add_f32_e32 v5, v89, v5
	v_exp_f32_e32 v93, v93
	v_sub_f32_e32 v94, v94, v193
	v_add_f32_e32 v5, v90, v5
	v_exp_f32_e32 v94, v94
	v_sub_f32_e32 v95, v95, v193
	v_add_f32_e32 v5, v91, v5
	v_exp_f32_e32 v95, v95
	v_add_f32_e32 v5, v92, v5
	v_add_f32_e32 v5, v93, v5
	v_add_f32_e32 v5, v94, v5
	v_add_f32_e32 v5, v95, v5
	v_add_f32_e32 v192, v192, v5
	v_cvt_pk_bf16_f32 v2, v0, v2
	v_cvt_pk_bf16_f32 v3, v3, v4
	v_cvt_pk_bf16_f32 v4, v6, v7
	v_cvt_pk_bf16_f32 v5, v8, v9
	v_cvt_pk_bf16_f32 v6, v10, v11
	v_cvt_pk_bf16_f32 v7, v12, v13
	v_cvt_pk_bf16_f32 v8, v14, v15
	v_cvt_pk_bf16_f32 v9, v96, v97
	v_cvt_pk_bf16_f32 v10, v80, v81
	v_cvt_pk_bf16_f32 v11, v82, v83
	v_cvt_pk_bf16_f32 v12, v84, v85
	v_cvt_pk_bf16_f32 v13, v86, v87
	v_cvt_pk_bf16_f32 v80, v88, v89
	v_cvt_pk_bf16_f32 v81, v90, v91
	v_cvt_pk_bf16_f32 v82, v92, v93
	v_cvt_pk_bf16_f32 v83, v94, v95
	v_add_u32_e32 v14, v246, v190
	v_add_u32_e32 v0, v246, v191
	s_waitcnt lgkmcnt(5)
	s_setprio 1
	v_mfma_f32_32x32x16_bf16 v[64:79], v[210:213], v[2:5], v[64:79]
	ds_read_b128 v[84:87], v248 offset:8192
	s_waitcnt lgkmcnt(5)
	v_mfma_f32_32x32x16_bf16 v[48:63], v[214:217], v[2:5], v[48:63]
	ds_read_b128 v[88:91], v248 offset:12288
	s_waitcnt lgkmcnt(5)
	v_mfma_f32_32x32x16_bf16 v[32:47], v[218:221], v[2:5], v[32:47]
	ds_read_b128 v[92:95], v14
	s_waitcnt lgkmcnt(5)
	v_mfma_f32_32x32x16_bf16 v[16:31], v[222:225], v[2:5], v[16:31]
	ds_read_b128 v[2:5], v14 offset:4096
	s_waitcnt lgkmcnt(5)
	v_mfma_f32_32x32x16_bf16 v[64:79], v[226:229], v[6:9], v[64:79]
	ds_read_b128 v[96:99], v14 offset:8192
	s_waitcnt lgkmcnt(5)
	v_mfma_f32_32x32x16_bf16 v[48:63], v[236:239], v[6:9], v[48:63]
	ds_read_b128 v[100:103], v14 offset:12288
	s_waitcnt lgkmcnt(5)
	v_mfma_f32_32x32x16_bf16 v[32:47], v[84:87], v[6:9], v[32:47]
	ds_read_b128 v[84:87], v0
	s_waitcnt lgkmcnt(5)
	v_mfma_f32_32x32x16_bf16 v[16:31], v[88:91], v[6:9], v[16:31]
	ds_read_b128 v[6:9], v0 offset:4096
	s_waitcnt lgkmcnt(5)
	v_mfma_f32_32x32x16_bf16 v[64:79], v[92:95], v[10:13], v[64:79]
	ds_read_b128 v[88:91], v0 offset:8192
	s_waitcnt lgkmcnt(5)
	v_mfma_f32_32x32x16_bf16 v[48:63], v[2:5], v[10:13], v[48:63]
	ds_read_b128 v[2:5], v0 offset:12288
	s_waitcnt lgkmcnt(5)
	v_mfma_f32_32x32x16_bf16 v[32:47], v[96:99], v[10:13], v[32:47]
	s_waitcnt lgkmcnt(4)
	v_mfma_f32_32x32x16_bf16 v[16:31], v[100:103], v[10:13], v[16:31]
	s_waitcnt lgkmcnt(3)
	v_mfma_f32_32x32x16_bf16 v[64:79], v[84:87], v[80:83], v[64:79]
	s_waitcnt lgkmcnt(2)
	v_mfma_f32_32x32x16_bf16 v[48:63], v[6:9], v[80:83], v[48:63]
	s_waitcnt lgkmcnt(1)
	v_mfma_f32_32x32x16_bf16 v[32:47], v[88:91], v[80:83], v[32:47]
	s_waitcnt lgkmcnt(0)
	v_mfma_f32_32x32x16_bf16 v[16:31], v[2:5], v[80:83], v[16:31]
	s_setprio 0
	s_mov_b64 s[16:17], -1
	s_and_b64 vcc, exec, s[14:15]
	s_cbranch_vccnz .LBB0_1208

; __device__ __forceinline__ unsigned cvt_pk_bf16(float lo, float hi) { unsigned r; asm volatile("v_cvt_pk_bf16_f32 %0, %1, %2" : "=v"(r) : "v"(lo), "v"(hi)); return r; }
; #define LAS __attribute__((address_space(3)))
; template <bool MLA, bool grpB>
; __device__ __forceinline__ void attn_unit_g(LAS unsigned char* lds, const AttnPtrs& P, int b, int h, int qblk) {
;     ...
;         float ps = 0.f;
; #pragma unroll
;         for (int blk = 0; blk < 2; ++blk)
; #pragma unroll
;             for (int r = 0; r < 16; ++r) { const float pv_ = __builtin_amdgcn_exp2f(sc[blk][r] - mref); sc[blk][r] = pv_; ps += pv_; }
;         lrun += ps;
; #pragma unroll
;         for (int blk = 0; blk < 2; ++blk)
; #pragma unroll
;             for (int ks = 0; ks < 2; ++ks) { u32x4 w;
;                 w.x = pg8::cvt_pk_bf16(sc[blk][8 * ks + 0], sc[blk][8 * ks + 1]); w.y = pg8::cvt_pk_bf16(sc[blk][8 * ks + 2], sc[blk][8 * ks + 3]);
;                 w.z = pg8::cvt_pk_bf16(sc[blk][8 * ks + 4], sc[blk][8 * ks + 5]); w.w = pg8::cvt_pk_bf16(sc[blk][8 * ks + 6], sc[blk][8 * ks + 7]);
;                 pb[blk][ks] = __builtin_bit_cast(bf16x8, w); }
;         __builtin_amdgcn_sched_barrier(0);
;     };
;     auto pv = [&](int voff) {
;         const LAS unsigned char* va = lds + varow + voff;
;         bf16x8 a[PFD];
;         auto ld = [&](int i) -> bf16x8 {
;             const int dvb = i & 3, bk = i >> 2, so = ((4 * (bk >> 1) + 2 * hi + (bk & 1)) ^ vswz) * 16;
;             return *(const LAS bf16x8*)(va + 32 * dvb * VROW + so);
;         };
; #pragma unroll
;         for (int i = 0; i < PFD; ++i) a[i] = ld(i);
; #pragma unroll
;         for (int i = 0; i < 16; ++i) {
;             o[i & 3] = __builtin_amdgcn_mfma_f32_32x32x16_bf16(a[i % PFD], pb[i >> 3][(i >> 2) & 1], o[i & 3], 0, 0, 0);
;             if (i + PFD < 16) a[i % PFD] = ld(i + PFD);
;         }
;         __builtin_amdgcn_sched_group_barrier(0x100, PFD, 0);
; #pragma unroll
;         for (int i = 0; i < 16; ++i) { __builtin_amdgcn_sched_group_barrier(0x008, 1, 0); __builtin_amdgcn_sched_group_barrier(0x100, 1, 0); }
;         __builtin_amdgcn_sched_barrier(0);
.LBB0_1319:
	v_add_u32_e32 v246, s41, v175
	v_add_u32_e32 v247, v246, v176
	ds_read_b128 v[210:213], v247
	ds_read_b128 v[214:217], v247 offset:4096
	ds_read_b128 v[218:221], v247 offset:8192
	ds_read_b128 v[222:225], v247 offset:12288
	v_add_u32_e32 v248, v246, v177
	ds_read_b128 v[226:229], v248
	ds_read_b128 v[236:239], v248 offset:4096
	v_sub_f32_e32 v0, v96, v181
	v_exp_f32_e32 v0, v0
	v_sub_f32_e32 v2, v97, v181
	v_exp_f32_e32 v2, v2
	v_sub_f32_e32 v3, v98, v181
	v_exp_f32_e32 v3, v3
	v_sub_f32_e32 v4, v99, v181
	v_exp_f32_e32 v4, v4
	v_sub_f32_e32 v6, v100, v181
	v_add_f32_e32 v5, 0, v0
	v_exp_f32_e32 v6, v6
	v_sub_f32_e32 v7, v101, v181
	v_add_f32_e32 v5, v2, v5
	v_exp_f32_e32 v7, v7
	v_sub_f32_e32 v8, v102, v181
	v_add_f32_e32 v5, v3, v5
	v_exp_f32_e32 v8, v8
	v_sub_f32_e32 v9, v103, v181
	v_add_f32_e32 v5, v4, v5
	v_exp_f32_e32 v9, v9
	v_sub_f32_e32 v10, v104, v181
	v_add_f32_e32 v5, v6, v5
	v_exp_f32_e32 v10, v10
	v_sub_f32_e32 v11, v105, v181
	v_add_f32_e32 v5, v7, v5
	v_exp_f32_e32 v11, v11
	v_sub_f32_e32 v12, v106, v181
	v_add_f32_e32 v5, v8, v5
	v_exp_f32_e32 v12, v12
	v_sub_f32_e32 v13, v107, v181
	v_add_f32_e32 v5, v9, v5
	v_exp_f32_e32 v13, v13
	v_sub_f32_e32 v14, v108, v181
	v_add_f32_e32 v5, v10, v5
	v_exp_f32_e32 v14, v14
	v_sub_f32_e32 v15, v109, v181
	v_add_f32_e32 v5, v11, v5
	v_exp_f32_e32 v15, v15
	v_sub_f32_e32 v96, v110, v181
	v_add_f32_e32 v5, v12, v5
	v_exp_f32_e32 v96, v96
	v_sub_f32_e32 v97, v111, v181
	v_add_f32_e32 v5, v13, v5
	v_exp_f32_e32 v97, v97
	v_sub_f32_e32 v80, v80, v181
	v_add_f32_e32 v5, v14, v5
	v_exp_f32_e32 v80, v80
	v_sub_f32_e32 v81, v81, v181
	v_add_f32_e32 v5, v15, v5
	v_exp_f32_e32 v81, v81
	v_sub_f32_e32 v82, v82, v181
	v_add_f32_e32 v5, v96, v5
	v_exp_f32_e32 v82, v82
	v_sub_f32_e32 v83, v83, v181
	v_add_f32_e32 v5, v97, v5
	v_exp_f32_e32 v83, v83
	v_sub_f32_e32 v84, v84, v181
	v_add_f32_e32 v5, v80, v5
	v_exp_f32_e32 v84, v84
	v_sub_f32_e32 v85, v85, v181
	v_add_f32_e32 v5, v81, v5
	v_exp_f32_e32 v85, v85
	v_sub_f32_e32 v86, v86, v181
	v_add_f32_e32 v5, v82, v5
	v_exp_f32_e32 v86, v86
	v_sub_f32_e32 v87, v87, v181
	v_add_f32_e32 v5, v83, v5
	v_exp_f32_e32 v87, v87
	v_sub_f32_e32 v88, v88, v181
	v_add_f32_e32 v5, v84, v5
	v_exp_f32_e32 v88, v88
	v_sub_f32_e32 v89, v89, v181
	v_add_f32_e32 v5, v85, v5
	v_exp_f32_e32 v89, v89
	v_sub_f32_e32 v90, v90, v181
	v_add_f32_e32 v5, v86, v5
	v_exp_f32_e32 v90, v90
	v_sub_f32_e32 v91, v91, v181
	v_add_f32_e32 v5, v87, v5
	v_exp_f32_e32 v91, v91
	v_sub_f32_e32 v92, v92, v181
	v_add_f32_e32 v5, v88, v5
	v_exp_f32_e32 v92, v92
	v_sub_f32_e32 v93, v93, v181
	v_add_f32_e32 v5, v89, v5
	v_exp_f32_e32 v93, v93
	v_sub_f32_e32 v94, v94, v181
	v_add_f32_e32 v5, v90, v5
	v_exp_f32_e32 v94, v94
	v_sub_f32_e32 v95, v95, v181
	v_add_f32_e32 v5, v91, v5
	v_exp_f32_e32 v95, v95
	v_add_f32_e32 v5, v92, v5
	v_add_f32_e32 v5, v93, v5
	v_add_f32_e32 v5, v94, v5
	v_add_f32_e32 v5, v95, v5
	v_add_f32_e32 v180, v180, v5
	v_cvt_pk_bf16_f32 v2, v0, v2
	v_cvt_pk_bf16_f32 v3, v3, v4
	v_cvt_pk_bf16_f32 v4, v6, v7
	v_cvt_pk_bf16_f32 v5, v8, v9
	v_cvt_pk_bf16_f32 v6, v10, v11
	v_cvt_pk_bf16_f32 v7, v12, v13
	v_cvt_pk_bf16_f32 v8, v14, v15
	v_cvt_pk_bf16_f32 v9, v96, v97
	v_cvt_pk_bf16_f32 v10, v80, v81
	v_cvt_pk_bf16_f32 v11, v82, v83
	v_cvt_pk_bf16_f32 v12, v84, v85
	v_cvt_pk_bf16_f32 v13, v86, v87
	v_cvt_pk_bf16_f32 v80, v88, v89
	v_cvt_pk_bf16_f32 v81, v90, v91
	v_cvt_pk_bf16_f32 v82, v92, v93
	v_cvt_pk_bf16_f32 v83, v94, v95
	v_add_u32_e32 v14, v246, v178
	v_add_u32_e32 v0, v246, v179
	s_waitcnt lgkmcnt(5)
	s_setprio 1
	v_mfma_f32_32x32x16_bf16 v[64:79], v[210:213], v[2:5], v[64:79]
	ds_read_b128 v[84:87], v248 offset:8192
	s_waitcnt lgkmcnt(5)
	v_mfma_f32_32x32x16_bf16 v[48:63], v[214:217], v[2:5], v[48:63]
	ds_read_b128 v[88:91], v248 offset:12288
	s_waitcnt lgkmcnt(5)
	v_mfma_f32_32x32x16_bf16 v[32:47], v[218:221], v[2:5], v[32:47]
	ds_read_b128 v[92:95], v14
	s_waitcnt lgkmcnt(5)
	v_mfma_f32_32x32x16_bf16 v[16:31], v[222:225], v[2:5], v[16:31]
	ds_read_b128 v[2:5], v14 offset:4096
	s_waitcnt lgkmcnt(5)
	v_mfma_f32_32x32x16_bf16 v[64:79], v[226:229], v[6:9], v[64:79]
	ds_read_b128 v[96:99], v14 offset:8192
	s_waitcnt lgkmcnt(5)
	v_mfma_f32_32x32x16_bf16 v[48:63], v[236:239], v[6:9], v[48:63]
	ds_read_b128 v[100:103], v14 offset:12288
	s_waitcnt lgkmcnt(5)
	v_mfma_f32_32x32x16_bf16 v[32:47], v[84:87], v[6:9], v[32:47]
	ds_read_b128 v[84:87], v0
	s_waitcnt lgkmcnt(5)
	v_mfma_f32_32x32x16_bf16 v[16:31], v[88:91], v[6:9], v[16:31]
	ds_read_b128 v[6:9], v0 offset:4096
	s_waitcnt lgkmcnt(5)
	v_mfma_f32_32x32x16_bf16 v[64:79], v[92:95], v[10:13], v[64:79]
	ds_read_b128 v[88:91], v0 offset:8192
	s_waitcnt lgkmcnt(5)
	v_mfma_f32_32x32x16_bf16 v[48:63], v[2:5], v[10:13], v[48:63]
	ds_read_b128 v[2:5], v0 offset:12288
	s_waitcnt lgkmcnt(5)
	v_mfma_f32_32x32x16_bf16 v[32:47], v[96:99], v[10:13], v[32:47]
	s_waitcnt lgkmcnt(4)
	v_mfma_f32_32x32x16_bf16 v[16:31], v[100:103], v[10:13], v[16:31]
	s_waitcnt lgkmcnt(3)
	v_mfma_f32_32x32x16_bf16 v[64:79], v[84:87], v[80:83], v[64:79]
	s_waitcnt lgkmcnt(2)
	v_mfma_f32_32x32x16_bf16 v[48:63], v[6:9], v[80:83], v[48:63]
	s_waitcnt lgkmcnt(1)
	v_mfma_f32_32x32x16_bf16 v[32:47], v[88:91], v[80:83], v[32:47]
	s_waitcnt lgkmcnt(0)
	v_mfma_f32_32x32x16_bf16 v[16:31], v[2:5], v[80:83], v[16:31]
	s_setprio 0
	s_mov_b64 s[8:9], -1
	s_and_b64 vcc, exec, s[74:75]
	s_cbranch_vccnz .LBB0_1325
